# attention: LDS fragment reads hoisted above preceding MFMA group into spare regs (40 groups)
# baseline (speedup 1.0000x reference)
.LBB0_1055:
	v_add3_u32 v83, s18, v186, v188
	ds_read_b128 v[212:215], v83 offset:128
	ds_read_b128 v[84:87], v83
	ds_read_b128 v[92:95], v83 offset:64
	s_waitcnt lgkmcnt(1)
	v_mfma_f32_16x16x32_bf16 v[88:91], v[84:87], v[0:3], 0
	ds_read_b128 v[98:101], v83 offset:3392
	ds_read_b128 v[102:105], v83 offset:6720
	ds_read_b128 v[156:159], v83 offset:10048
	v_mfma_f32_16x16x32_bf16 v[84:87], v[84:87], v[12:15], 0
	ds_read_b128 v[216:219], v83 offset:3328
	s_waitcnt lgkmcnt(3)
	v_mfma_f32_16x16x32_bf16 v[88:91], v[92:95], v[4:7], v[88:91]
	v_mfma_f32_16x16x32_bf16 v[84:87], v[92:95], v[16:19], v[84:87]
	s_waitcnt lgkmcnt(0)
	v_mfma_f32_16x16x32_bf16 v[160:163], v[212:215], v[8:11], v[88:91]
	v_mfma_f32_16x16x32_bf16 v[90:93], v[212:215], v[20:23], v[84:87]
	ds_read_b128 v[212:215], v83 offset:3456
	s_nop 3
	s_waitcnt lgkmcnt(0)
	v_mfma_f32_16x16x32_bf16 v[94:97], v[216:219], v[0:3], 0
	s_nop 0
	v_max_f32_e32 v153, v91, v91
	v_mfma_f32_16x16x32_bf16 v[84:87], v[216:219], v[12:15], 0
	ds_read_b128 v[216:219], v83 offset:6656
	v_mfma_f32_16x16x32_bf16 v[94:97], v[98:101], v[4:7], v[94:97]
	v_mfma_f32_16x16x32_bf16 v[84:87], v[98:101], v[16:19], v[84:87]
	s_waitcnt lgkmcnt(0)
	v_mfma_f32_16x16x32_bf16 v[166:169], v[212:215], v[8:11], v[94:97]
	v_mfma_f32_16x16x32_bf16 v[94:97], v[212:215], v[20:23], v[84:87]
	ds_read_b128 v[212:215], v83 offset:6784
	s_nop 3
	s_waitcnt lgkmcnt(0)
	v_mfma_f32_16x16x32_bf16 v[98:101], v[216:219], v[0:3], 0
	v_mfma_f32_16x16x32_bf16 v[84:87], v[216:219], v[12:15], 0
	ds_read_b128 v[216:219], v83 offset:9984
	v_mfma_f32_16x16x32_bf16 v[98:101], v[102:105], v[4:7], v[98:101]
	v_mfma_f32_16x16x32_bf16 v[84:87], v[102:105], v[16:19], v[84:87]
	s_waitcnt lgkmcnt(0)
	v_mfma_f32_16x16x32_bf16 v[174:177], v[212:215], v[8:11], v[98:101]
	v_mfma_f32_16x16x32_bf16 v[98:101], v[212:215], v[20:23], v[84:87]
	s_nop 3
	s_waitcnt lgkmcnt(0)
	v_mfma_f32_16x16x32_bf16 v[102:105], v[216:219], v[0:3], 0
	v_mfma_f32_16x16x32_bf16 v[84:87], v[216:219], v[12:15], 0
	v_mfma_f32_16x16x32_bf16 v[102:105], v[156:159], v[4:7], v[102:105]
	v_mfma_f32_16x16x32_bf16 v[84:87], v[156:159], v[16:19], v[84:87]
	ds_read_b128 v[156:159], v83 offset:10112
	v_max_f32_e32 v83, v161, v161
	s_waitcnt lgkmcnt(0)
	v_mfma_f32_16x16x32_bf16 v[192:195], v[156:159], v[8:11], v[102:105]
	v_mfma_f32_16x16x32_bf16 v[102:105], v[156:159], v[20:23], v[84:87]
	v_max_f32_e32 v157, v90, v90
	v_max_f32_e32 v153, v157, v153
	v_max_f32_e32 v157, v93, v93
	v_max_f32_e32 v84, v160, v160
	v_max_f32_e32 v83, v84, v83
	v_max_f32_e32 v84, v163, v163
	v_max_f32_e32 v85, v162, v162
	v_max_f32_e32 v84, v85, v84
	v_max_f32_e32 v85, v169, v169
	v_max_f32_e32 v86, v168, v168
	v_max_f32_e32 v85, v86, v85
	v_max3_f32 v85, v166, v167, v85
	v_max3_f32 v83, v83, v84, v85
	v_max_f32_e32 v84, v177, v177
	v_max_f32_e32 v85, v176, v176
	v_max_f32_e32 v84, v85, v84
	v_max_f32_e32 v85, v195, v195
	v_max_f32_e32 v86, v194, v194
	v_max_f32_e32 v85, v86, v85
	v_max3_f32 v84, v174, v175, v84
	v_max3_f32 v85, v192, v193, v85
	v_max3_f32 v83, v83, v84, v85
	s_waitcnt lgkmcnt(0)
	v_max_f32_e32 v84, v84, v84
	v_mov_b32_e32 v84, v83
	s_nop 1
	v_permlane16_swap_b32_e32 v83, v84
	v_max_f32_e32 v83, v83, v84
	v_mov_b32_e32 v84, v83
	s_nop 1
	v_permlane32_swap_b32_e32 v83, v84
	v_max3_f32 v143, v82, v83, v84
	v_sub_f32_e32 v82, v82, v143
	v_exp_f32_e32 v158, v82
	v_sub_f32_e32 v82, v160, v143
	v_exp_f32_e32 v152, v82
	v_sub_f32_e32 v82, v161, v143
	v_exp_f32_e32 v156, v82
	v_sub_f32_e32 v82, v162, v143
	v_exp_f32_e32 v160, v82
	v_sub_f32_e32 v82, v163, v143
	v_exp_f32_e32 v162, v82
	v_sub_f32_e32 v82, v166, v143
	v_exp_f32_e32 v164, v82
	v_sub_f32_e32 v82, v167, v143
	v_exp_f32_e32 v166, v82
	v_sub_f32_e32 v82, v168, v143
	v_exp_f32_e32 v168, v82
	v_sub_f32_e32 v82, v169, v143
	v_exp_f32_e32 v170, v82
	v_sub_f32_e32 v82, v174, v143
	v_exp_f32_e32 v172, v82
	v_sub_f32_e32 v82, v175, v143
	v_exp_f32_e32 v174, v82
	v_sub_f32_e32 v82, v176, v143
	v_exp_f32_e32 v176, v82
	v_sub_f32_e32 v82, v177, v143
	v_exp_f32_e32 v178, v82
	v_sub_f32_e32 v82, v192, v143
	v_exp_f32_e32 v180, v82
	v_sub_f32_e32 v82, v193, v143
	v_exp_f32_e32 v182, v82
	v_sub_f32_e32 v82, v194, v143
	v_exp_f32_e32 v192, v82
	v_sub_f32_e32 v82, v195, v143
	v_exp_f32_e32 v194, v82
	v_pk_mul_f32 v[84:85], v[68:69], v[158:159] op_sel_hi:[1,0]
	v_pk_mul_f32 v[82:83], v[66:67], v[158:159] op_sel_hi:[1,0]
	v_pk_mul_f32 v[88:89], v[72:73], v[158:159] op_sel_hi:[1,0]
	v_pk_mul_f32 v[86:87], v[70:71], v[158:159] op_sel_hi:[1,0]
	v_pk_mul_f32 v[76:77], v[76:77], v[158:159] op_sel_hi:[1,0]
	v_pk_mul_f32 v[74:75], v[74:75], v[158:159] op_sel_hi:[1,0]
	v_pk_mul_f32 v[68:69], v[80:81], v[158:159] op_sel_hi:[1,0]
	v_pk_mul_f32 v[66:67], v[78:79], v[158:159] op_sel_hi:[1,0]
	v_max_f32_e32 v159, v92, v92
	v_max_f32_e32 v157, v159, v157
	v_max_f32_e32 v159, v97, v97
	v_max_f32_e32 v161, v96, v96
	v_max_f32_e32 v159, v161, v159
	v_max3_f32 v159, v94, v95, v159
	v_max3_f32 v153, v153, v157, v159
	v_max_f32_e32 v157, v101, v101
	v_max_f32_e32 v159, v100, v100
	v_max_f32_e32 v157, v159, v157
	v_max_f32_e32 v159, v105, v105
	v_max_f32_e32 v161, v104, v104
	v_max_f32_e32 v159, v161, v159
	v_max3_f32 v157, v98, v99, v157
	v_max3_f32 v159, v102, v103, v159
	v_max3_f32 v153, v153, v157, v159
	v_cvt_pk_bf16_f32 v70, v152, v156
	v_cvt_pk_bf16_f32 v71, v160, v162
	v_cvt_pk_bf16_f32 v72, v164, v166
	v_cvt_pk_bf16_f32 v73, v168, v170
	s_waitcnt lgkmcnt(0)
	v_max_f32_e32 v157, v157, v157
	v_mov_b32_e32 v157, v153
	s_nop 1
	v_permlane16_swap_b32_e32 v153, v157
	v_max_f32_e32 v153, v153, v157
	v_mov_b32_e32 v157, v153
	s_nop 1
	v_permlane32_swap_b32_e32 v153, v157
	v_max3_f32 v191, v127, v153, v157
	v_sub_f32_e32 v90, v90, v191
	v_exp_f32_e32 v153, v90
	v_sub_f32_e32 v90, v91, v191
	v_exp_f32_e32 v157, v90
	v_sub_f32_e32 v90, v92, v191
	v_exp_f32_e32 v161, v90
	v_sub_f32_e32 v90, v93, v191
	v_exp_f32_e32 v163, v90
	v_sub_f32_e32 v90, v94, v191
	v_exp_f32_e32 v165, v90
	v_sub_f32_e32 v90, v95, v191
	v_exp_f32_e32 v167, v90
	v_pk_add_f32 v[90:91], v[152:153], 0 op_sel_hi:[1,0]
	v_sub_f32_e32 v92, v96, v191
	v_pk_add_f32 v[90:91], v[156:157], v[90:91]
	v_exp_f32_e32 v169, v92
	v_pk_add_f32 v[90:91], v[160:161], v[90:91]
	v_sub_f32_e32 v92, v97, v191
	v_pk_add_f32 v[90:91], v[162:163], v[90:91]
	v_exp_f32_e32 v171, v92
	v_sub_f32_e32 v92, v98, v191
	v_pk_add_f32 v[90:91], v[164:165], v[90:91]
	v_exp_f32_e32 v173, v92
	v_sub_f32_e32 v92, v99, v191
	v_pk_add_f32 v[90:91], v[166:167], v[90:91]
	v_exp_f32_e32 v175, v92
	v_sub_f32_e32 v92, v100, v191
	v_exp_f32_e32 v177, v92
	v_sub_f32_e32 v92, v101, v191
	v_pk_add_f32 v[90:91], v[168:169], v[90:91]
	v_exp_f32_e32 v179, v92
	v_sub_f32_e32 v92, v102, v191
	v_pk_add_f32 v[90:91], v[170:171], v[90:91]
	v_exp_f32_e32 v181, v92
	v_sub_f32_e32 v92, v103, v191
	v_pk_add_f32 v[90:91], v[172:173], v[90:91]
	v_exp_f32_e32 v183, v92
	v_sub_f32_e32 v92, v104, v191
	v_pk_add_f32 v[90:91], v[174:175], v[90:91]
	v_sub_f32_e32 v127, v127, v191
	v_exp_f32_e32 v193, v92
	v_sub_f32_e32 v92, v105, v191
	v_pk_add_f32 v[90:91], v[176:177], v[90:91]
	v_exp_f32_e32 v159, v127
	v_exp_f32_e32 v195, v92
	v_pk_add_f32 v[90:91], v[178:179], v[90:91]
	v_cvt_pk_bf16_f32 v78, v172, v174
	v_pk_add_f32 v[90:91], v[180:181], v[90:91]
	v_mov_b32_e32 v98, v159
	v_pk_add_f32 v[90:91], v[182:183], v[90:91]
	v_pk_mul_f32 v[92:93], v[52:53], v[98:99] op_sel_hi:[1,0]
	v_pk_add_f32 v[90:91], v[192:193], v[90:91]
	v_pk_mul_f32 v[96:97], v[56:57], v[98:99] op_sel_hi:[1,0]
	v_pk_add_f32 v[90:91], v[194:195], v[90:91]
	v_pk_mul_f32 v[94:95], v[54:55], v[98:99] op_sel_hi:[1,0]
	v_pk_fma_f32 v[150:151], v[150:151], v[158:159], v[90:91]
	v_pk_mul_f32 v[90:91], v[50:51], v[98:99] op_sel_hi:[1,0]
	v_pk_mul_f32 v[60:61], v[60:61], v[98:99] op_sel_hi:[1,0]
	v_pk_mul_f32 v[58:59], v[58:59], v[98:99] op_sel_hi:[1,0]
	v_pk_mul_f32 v[52:53], v[64:65], v[98:99] op_sel_hi:[1,0]
	v_pk_mul_f32 v[50:51], v[62:63], v[98:99] op_sel_hi:[1,0]
	v_lshlrev_b32_e32 v98, 1, v187
	v_add3_u32 v127, s18, v98, v189
	ds_read_b64_tr_b16 v[216:217], v127 offset:13384
	ds_read_b64_tr_b16 v[218:219], v127 offset:15944
	ds_read_b64_tr_b16 v[212:213], v127 offset:13376
	ds_read_b64_tr_b16 v[214:215], v127 offset:15936
	ds_read_b64_tr_b16 v[100:101], v127 offset:15872
	ds_read_b64_tr_b16 v[98:99], v127 offset:13312
	ds_read_b64_tr_b16 v[102:103], v127 offset:13320
	v_cvt_pk_bf16_f32 v54, v153, v157
	v_cvt_pk_bf16_f32 v55, v161, v163
	v_cvt_pk_bf16_f32 v56, v165, v167
	v_cvt_pk_bf16_f32 v57, v169, v171
	s_waitcnt lgkmcnt(1)
	v_mfma_f32_16x16x32_bf16 v[82:85], v[98:101], v[70:73], v[82:85]
	ds_read_b64_tr_b16 v[104:105], v127 offset:15880
	v_cvt_pk_bf16_f32 v79, v176, v178
	v_cvt_pk_bf16_f32 v80, v180, v182
	v_mfma_f32_16x16x32_bf16 v[90:93], v[98:101], v[54:57], v[90:93]
	v_cvt_pk_bf16_f32 v81, v192, v194
	v_cvt_pk_bf16_f32 v62, v173, v175
	s_waitcnt lgkmcnt(0)
	v_mfma_f32_16x16x32_bf16 v[74:77], v[212:215], v[70:73], v[74:77]
	v_cvt_pk_bf16_f32 v63, v177, v179
	v_cvt_pk_bf16_f32 v64, v181, v183
	v_cvt_pk_bf16_f32 v65, v193, v195
	v_mfma_f32_16x16x32_bf16 v[58:61], v[212:215], v[54:57], v[58:61]
	ds_read_b64_tr_b16 v[212:213], v127 offset:18432
	ds_read_b64_tr_b16 v[214:215], v127 offset:20992
	v_mfma_f32_16x16x32_bf16 v[86:89], v[102:105], v[70:73], v[86:89]
	ds_read_b64_tr_b16 v[220:221], v127 offset:18496
	ds_read_b64_tr_b16 v[222:223], v127 offset:21056
	v_mfma_f32_16x16x32_bf16 v[94:97], v[102:105], v[54:57], v[94:97]
	s_waitcnt lgkmcnt(0)
	v_mfma_f32_16x16x32_bf16 v[102:105], v[216:219], v[70:73], v[66:69]
	v_mfma_f32_16x16x32_bf16 v[98:101], v[216:219], v[54:57], v[50:53]
	s_nop 2
	ds_read_b64_tr_b16 v[54:55], v127 offset:18440
	ds_read_b64_tr_b16 v[56:57], v127 offset:21000
	s_waitcnt lgkmcnt(2)
	v_mfma_f32_16x16x32_bf16 v[66:69], v[212:215], v[78:81], v[82:85]
	s_nop 2
	s_waitcnt lgkmcnt(0)
	v_mfma_f32_16x16x32_bf16 v[74:77], v[220:223], v[78:81], v[74:77]
	v_mfma_f32_16x16x32_bf16 v[58:61], v[220:223], v[62:65], v[58:61]
	ds_read_b64_tr_b16 v[82:83], v127 offset:18504
	ds_read_b64_tr_b16 v[84:85], v127 offset:21064
	v_mov_b32_e32 v127, v191
	v_mfma_f32_16x16x32_bf16 v[50:53], v[212:215], v[62:65], v[90:93]
	v_mfma_f32_16x16x32_bf16 v[70:73], v[54:57], v[78:81], v[86:89]
	v_mfma_f32_16x16x32_bf16 v[54:57], v[54:57], v[62:65], v[94:97]
	s_waitcnt lgkmcnt(0)
	v_mfma_f32_16x16x32_bf16 v[78:81], v[82:85], v[78:81], v[102:105]
	v_mfma_f32_16x16x32_bf16 v[62:65], v[82:85], v[62:65], v[98:101]
	v_mov_b32_e32 v82, v143
	s_add_i32 s6, s48, -2
	s_cmp_ge_i32 s6, s47
	s_cbranch_scc1 .LBB0_1042
.LBB0_1056:
	s_and_b32 s6, s6, 3
	s_mulk_i32 s6, 0x5c00
	s_add_i32 s18, s6, 0
	v_add3_u32 v83, s18, v186, v188
	ds_read_b128 v[212:215], v83 offset:128
	ds_read_b128 v[84:87], v83
	ds_read_b128 v[92:95], v83 offset:64
	s_waitcnt lgkmcnt(1)
	v_mfma_f32_16x16x32_bf16 v[88:91], v[84:87], v[0:3], 0
	ds_read_b128 v[98:101], v83 offset:3392
	ds_read_b128 v[102:105], v83 offset:6720
	ds_read_b128 v[156:159], v83 offset:10048
	v_mfma_f32_16x16x32_bf16 v[84:87], v[84:87], v[12:15], 0
	ds_read_b128 v[216:219], v83 offset:3328
	s_waitcnt lgkmcnt(3)
	v_mfma_f32_16x16x32_bf16 v[88:91], v[92:95], v[4:7], v[88:91]
	v_mfma_f32_16x16x32_bf16 v[84:87], v[92:95], v[16:19], v[84:87]
	s_waitcnt lgkmcnt(0)
	v_mfma_f32_16x16x32_bf16 v[160:163], v[212:215], v[8:11], v[88:91]
	v_mfma_f32_16x16x32_bf16 v[90:93], v[212:215], v[20:23], v[84:87]
	ds_read_b128 v[212:215], v83 offset:3456
	s_nop 3
	s_waitcnt lgkmcnt(0)
	v_mfma_f32_16x16x32_bf16 v[94:97], v[216:219], v[0:3], 0
	s_nop 0
	v_max_f32_e32 v153, v91, v91
	v_mfma_f32_16x16x32_bf16 v[84:87], v[216:219], v[12:15], 0
	ds_read_b128 v[216:219], v83 offset:6656
	v_mfma_f32_16x16x32_bf16 v[94:97], v[98:101], v[4:7], v[94:97]
	v_mfma_f32_16x16x32_bf16 v[84:87], v[98:101], v[16:19], v[84:87]
	s_waitcnt lgkmcnt(0)
	v_mfma_f32_16x16x32_bf16 v[166:169], v[212:215], v[8:11], v[94:97]
	v_mfma_f32_16x16x32_bf16 v[94:97], v[212:215], v[20:23], v[84:87]
	ds_read_b128 v[212:215], v83 offset:6784
	s_nop 3
	s_waitcnt lgkmcnt(0)
	v_mfma_f32_16x16x32_bf16 v[98:101], v[216:219], v[0:3], 0
	v_mfma_f32_16x16x32_bf16 v[84:87], v[216:219], v[12:15], 0
	ds_read_b128 v[216:219], v83 offset:9984
	v_mfma_f32_16x16x32_bf16 v[98:101], v[102:105], v[4:7], v[98:101]
	v_mfma_f32_16x16x32_bf16 v[84:87], v[102:105], v[16:19], v[84:87]
	s_waitcnt lgkmcnt(0)
	v_mfma_f32_16x16x32_bf16 v[174:177], v[212:215], v[8:11], v[98:101]
	v_mfma_f32_16x16x32_bf16 v[98:101], v[212:215], v[20:23], v[84:87]
	s_nop 3
	s_waitcnt lgkmcnt(0)
	v_mfma_f32_16x16x32_bf16 v[102:105], v[216:219], v[0:3], 0
	v_mfma_f32_16x16x32_bf16 v[84:87], v[216:219], v[12:15], 0
	v_mfma_f32_16x16x32_bf16 v[102:105], v[156:159], v[4:7], v[102:105]
	v_mfma_f32_16x16x32_bf16 v[84:87], v[156:159], v[16:19], v[84:87]
	ds_read_b128 v[156:159], v83 offset:10112
	v_max_f32_e32 v83, v161, v161
	s_waitcnt lgkmcnt(0)
	v_mfma_f32_16x16x32_bf16 v[180:183], v[156:159], v[8:11], v[102:105]
	v_mfma_f32_16x16x32_bf16 v[102:105], v[156:159], v[20:23], v[84:87]
	v_max_f32_e32 v157, v90, v90
	v_max_f32_e32 v153, v157, v153
	v_max_f32_e32 v157, v93, v93
	v_max_f32_e32 v84, v160, v160
	v_max_f32_e32 v83, v84, v83
	v_max_f32_e32 v84, v163, v163
	v_max_f32_e32 v85, v162, v162
	v_max_f32_e32 v84, v85, v84
	v_max_f32_e32 v85, v169, v169
	v_max_f32_e32 v86, v168, v168
	v_max_f32_e32 v85, v86, v85
	v_max3_f32 v85, v166, v167, v85
	v_max3_f32 v83, v83, v84, v85
	v_max_f32_e32 v84, v177, v177
	v_max_f32_e32 v85, v176, v176
	v_max_f32_e32 v84, v85, v84
	v_max_f32_e32 v85, v183, v183
	v_max_f32_e32 v86, v182, v182
	v_max_f32_e32 v85, v86, v85
	v_max3_f32 v84, v174, v175, v84
	v_max3_f32 v85, v180, v181, v85
	v_max3_f32 v83, v83, v84, v85
	s_waitcnt lgkmcnt(0)
	v_max_f32_e32 v84, v84, v84
	v_mov_b32_e32 v84, v83
	s_nop 1
	v_permlane16_swap_b32_e32 v83, v84
	v_max_f32_e32 v83, v83, v84
	v_mov_b32_e32 v84, v83
	s_nop 1
	v_permlane32_swap_b32_e32 v83, v84
	v_max3_f32 v143, v82, v83, v84
	v_sub_f32_e32 v82, v82, v143
	v_exp_f32_e32 v158, v82
	v_sub_f32_e32 v82, v160, v143
	v_exp_f32_e32 v152, v82
	v_sub_f32_e32 v82, v161, v143
	v_exp_f32_e32 v156, v82
	v_sub_f32_e32 v82, v162, v143
	v_exp_f32_e32 v160, v82
	v_sub_f32_e32 v82, v163, v143
	v_exp_f32_e32 v162, v82
	v_sub_f32_e32 v82, v166, v143
	v_exp_f32_e32 v164, v82
	v_sub_f32_e32 v82, v167, v143
	v_exp_f32_e32 v166, v82
	v_sub_f32_e32 v82, v168, v143
	v_exp_f32_e32 v168, v82
	v_sub_f32_e32 v82, v169, v143
	v_exp_f32_e32 v170, v82
	v_sub_f32_e32 v82, v174, v143
	v_exp_f32_e32 v172, v82
	v_sub_f32_e32 v82, v175, v143
	v_exp_f32_e32 v174, v82
	v_sub_f32_e32 v82, v176, v143
	v_exp_f32_e32 v176, v82
	v_sub_f32_e32 v82, v177, v143
	v_exp_f32_e32 v178, v82
	v_sub_f32_e32 v82, v180, v143
	v_exp_f32_e32 v180, v82
	v_sub_f32_e32 v82, v181, v143
	v_exp_f32_e32 v192, v82
	v_sub_f32_e32 v82, v182, v143
	v_exp_f32_e32 v194, v82
	v_sub_f32_e32 v82, v183, v143
	v_exp_f32_e32 v196, v82
	v_pk_mul_f32 v[84:85], v[68:69], v[158:159] op_sel_hi:[1,0]
	v_pk_mul_f32 v[82:83], v[66:67], v[158:159] op_sel_hi:[1,0]
	v_pk_mul_f32 v[88:89], v[72:73], v[158:159] op_sel_hi:[1,0]
	v_pk_mul_f32 v[86:87], v[70:71], v[158:159] op_sel_hi:[1,0]
	v_pk_mul_f32 v[76:77], v[76:77], v[158:159] op_sel_hi:[1,0]
	v_pk_mul_f32 v[74:75], v[74:75], v[158:159] op_sel_hi:[1,0]
	v_pk_mul_f32 v[68:69], v[80:81], v[158:159] op_sel_hi:[1,0]
	v_pk_mul_f32 v[66:67], v[78:79], v[158:159] op_sel_hi:[1,0]
	v_max_f32_e32 v159, v92, v92
	v_max_f32_e32 v157, v159, v157
	v_max_f32_e32 v159, v97, v97
	v_max_f32_e32 v161, v96, v96
	v_max_f32_e32 v159, v161, v159
	v_max3_f32 v159, v94, v95, v159
	v_max3_f32 v153, v153, v157, v159
	v_max_f32_e32 v157, v101, v101
	v_max_f32_e32 v159, v100, v100
	v_max_f32_e32 v157, v159, v157
	v_max_f32_e32 v159, v105, v105
	v_max_f32_e32 v161, v104, v104
	v_max_f32_e32 v159, v161, v159
	v_max3_f32 v157, v98, v99, v157
	v_max3_f32 v159, v102, v103, v159
	v_max3_f32 v153, v153, v157, v159
	v_cvt_pk_bf16_f32 v70, v152, v156
	v_cvt_pk_bf16_f32 v71, v160, v162
	v_cvt_pk_bf16_f32 v72, v164, v166
	v_cvt_pk_bf16_f32 v73, v168, v170
	s_waitcnt lgkmcnt(0)
	v_max_f32_e32 v157, v157, v157
	v_mov_b32_e32 v157, v153
	s_nop 1
	v_permlane16_swap_b32_e32 v153, v157
	v_max_f32_e32 v153, v153, v157
	v_mov_b32_e32 v157, v153
	s_nop 1
	v_permlane32_swap_b32_e32 v153, v157
	v_max3_f32 v182, v127, v153, v157
	v_sub_f32_e32 v90, v90, v182
	v_exp_f32_e32 v153, v90
	v_sub_f32_e32 v90, v91, v182
	v_exp_f32_e32 v157, v90
	v_sub_f32_e32 v90, v92, v182
	v_exp_f32_e32 v161, v90
	v_sub_f32_e32 v90, v93, v182
	v_exp_f32_e32 v163, v90
	v_sub_f32_e32 v90, v94, v182
	v_exp_f32_e32 v165, v90
	v_sub_f32_e32 v90, v95, v182
	v_exp_f32_e32 v167, v90
	v_pk_add_f32 v[90:91], v[152:153], 0 op_sel_hi:[1,0]
	v_sub_f32_e32 v92, v96, v182
	v_pk_add_f32 v[90:91], v[156:157], v[90:91]
	v_exp_f32_e32 v169, v92
	v_pk_add_f32 v[90:91], v[160:161], v[90:91]
	v_sub_f32_e32 v92, v97, v182
	v_pk_add_f32 v[90:91], v[162:163], v[90:91]
	v_exp_f32_e32 v171, v92
	v_sub_f32_e32 v92, v98, v182
	v_pk_add_f32 v[90:91], v[164:165], v[90:91]
	v_exp_f32_e32 v173, v92
	v_sub_f32_e32 v92, v99, v182
	v_pk_add_f32 v[90:91], v[166:167], v[90:91]
	v_exp_f32_e32 v175, v92
	v_sub_f32_e32 v92, v100, v182
	v_exp_f32_e32 v177, v92
	v_sub_f32_e32 v92, v101, v182
	v_pk_add_f32 v[90:91], v[168:169], v[90:91]
	v_exp_f32_e32 v179, v92
	v_sub_f32_e32 v92, v102, v182
	v_pk_add_f32 v[90:91], v[170:171], v[90:91]
	v_exp_f32_e32 v181, v92
	v_sub_f32_e32 v92, v103, v182
	v_pk_add_f32 v[90:91], v[172:173], v[90:91]
	v_exp_f32_e32 v193, v92
	v_sub_f32_e32 v92, v104, v182
	v_pk_add_f32 v[90:91], v[174:175], v[90:91]
	v_sub_f32_e32 v127, v127, v182
	v_exp_f32_e32 v195, v92
	v_sub_f32_e32 v92, v105, v182
	v_pk_add_f32 v[90:91], v[176:177], v[90:91]
	v_exp_f32_e32 v159, v127
	v_exp_f32_e32 v197, v92
	v_pk_add_f32 v[90:91], v[178:179], v[90:91]
	v_cvt_pk_bf16_f32 v78, v172, v174
	v_pk_add_f32 v[90:91], v[180:181], v[90:91]
	v_mov_b32_e32 v98, v159
	v_pk_add_f32 v[90:91], v[192:193], v[90:91]
	v_pk_mul_f32 v[92:93], v[52:53], v[98:99] op_sel_hi:[1,0]
	v_pk_add_f32 v[90:91], v[194:195], v[90:91]
	v_pk_mul_f32 v[96:97], v[56:57], v[98:99] op_sel_hi:[1,0]
	v_pk_add_f32 v[90:91], v[196:197], v[90:91]
	v_pk_mul_f32 v[94:95], v[54:55], v[98:99] op_sel_hi:[1,0]
	v_pk_fma_f32 v[150:151], v[150:151], v[158:159], v[90:91]
	v_pk_mul_f32 v[90:91], v[50:51], v[98:99] op_sel_hi:[1,0]
	v_pk_mul_f32 v[60:61], v[60:61], v[98:99] op_sel_hi:[1,0]
	v_pk_mul_f32 v[58:59], v[58:59], v[98:99] op_sel_hi:[1,0]
	v_pk_mul_f32 v[52:53], v[64:65], v[98:99] op_sel_hi:[1,0]
	v_pk_mul_f32 v[50:51], v[62:63], v[98:99] op_sel_hi:[1,0]
	v_lshlrev_b32_e32 v98, 1, v187
	v_add3_u32 v127, s18, v98, v189
	ds_read_b64_tr_b16 v[216:217], v127 offset:13384
	ds_read_b64_tr_b16 v[218:219], v127 offset:15944
	ds_read_b64_tr_b16 v[212:213], v127 offset:13376
	ds_read_b64_tr_b16 v[214:215], v127 offset:15936
	ds_read_b64_tr_b16 v[100:101], v127 offset:15872
	ds_read_b64_tr_b16 v[98:99], v127 offset:13312
	ds_read_b64_tr_b16 v[102:103], v127 offset:13320
	v_cvt_pk_bf16_f32 v54, v153, v157
	v_cvt_pk_bf16_f32 v55, v161, v163
	v_cvt_pk_bf16_f32 v56, v165, v167
	v_cvt_pk_bf16_f32 v57, v169, v171
	s_waitcnt lgkmcnt(1)
	v_mfma_f32_16x16x32_bf16 v[82:85], v[98:101], v[70:73], v[82:85]
	ds_read_b64_tr_b16 v[104:105], v127 offset:15880
	v_cvt_pk_bf16_f32 v79, v176, v178
	v_cvt_pk_bf16_f32 v80, v180, v192
	v_mfma_f32_16x16x32_bf16 v[90:93], v[98:101], v[54:57], v[90:93]
	v_cvt_pk_bf16_f32 v81, v194, v196
	v_cvt_pk_bf16_f32 v62, v173, v175
	s_waitcnt lgkmcnt(0)
	v_mfma_f32_16x16x32_bf16 v[74:77], v[212:215], v[70:73], v[74:77]
	v_cvt_pk_bf16_f32 v63, v177, v179
	v_cvt_pk_bf16_f32 v64, v181, v193
	v_cvt_pk_bf16_f32 v65, v195, v197
	v_mfma_f32_16x16x32_bf16 v[58:61], v[212:215], v[54:57], v[58:61]
	ds_read_b64_tr_b16 v[212:213], v127 offset:18432
	ds_read_b64_tr_b16 v[214:215], v127 offset:20992
	v_mfma_f32_16x16x32_bf16 v[86:89], v[102:105], v[70:73], v[86:89]
	ds_read_b64_tr_b16 v[220:221], v127 offset:18496
	ds_read_b64_tr_b16 v[222:223], v127 offset:21056
	v_mfma_f32_16x16x32_bf16 v[94:97], v[102:105], v[54:57], v[94:97]
	s_waitcnt lgkmcnt(0)
	v_mfma_f32_16x16x32_bf16 v[102:105], v[216:219], v[70:73], v[66:69]
	v_mfma_f32_16x16x32_bf16 v[98:101], v[216:219], v[54:57], v[50:53]
	s_nop 2
	ds_read_b64_tr_b16 v[54:55], v127 offset:18440
	ds_read_b64_tr_b16 v[56:57], v127 offset:21000
	s_waitcnt lgkmcnt(2)
	v_mfma_f32_16x16x32_bf16 v[66:69], v[212:215], v[78:81], v[82:85]
	s_nop 2
	s_waitcnt lgkmcnt(0)
	v_mfma_f32_16x16x32_bf16 v[74:77], v[220:223], v[78:81], v[74:77]
	v_mfma_f32_16x16x32_bf16 v[58:61], v[220:223], v[62:65], v[58:61]
	ds_read_b64_tr_b16 v[82:83], v127 offset:18504
	ds_read_b64_tr_b16 v[84:85], v127 offset:21064
	v_mov_b32_e32 v127, v182
	v_mfma_f32_16x16x32_bf16 v[50:53], v[212:215], v[62:65], v[90:93]
	v_mfma_f32_16x16x32_bf16 v[70:73], v[54:57], v[78:81], v[86:89]
	v_mfma_f32_16x16x32_bf16 v[54:57], v[54:57], v[62:65], v[94:97]
	s_waitcnt lgkmcnt(0)
	v_mfma_f32_16x16x32_bf16 v[78:81], v[82:85], v[78:81], v[102:105]
	v_mfma_f32_16x16x32_bf16 v[62:65], v[82:85], v[62:65], v[98:101]
	v_mov_b32_e32 v82, v143
	s_branch .LBB0_1042

.LBB0_1077:
	v_add3_u32 v83, s18, v186, v188
	ds_read_b128 v[212:215], v83 offset:128
	ds_read_b128 v[84:87], v83
	ds_read_b128 v[92:95], v83 offset:64
	s_waitcnt lgkmcnt(1)
	v_mfma_f32_16x16x32_bf16 v[88:91], v[84:87], v[8:11], 0
	ds_read_b128 v[98:101], v83 offset:3392
	ds_read_b128 v[102:105], v83 offset:6720
	ds_read_b128 v[144:147], v83 offset:10048
	v_mfma_f32_16x16x32_bf16 v[84:87], v[84:87], v[12:15], 0
	ds_read_b128 v[216:219], v83 offset:3328
	s_waitcnt lgkmcnt(3)
	v_mfma_f32_16x16x32_bf16 v[88:91], v[92:95], v[0:3], v[88:91]
	v_mfma_f32_16x16x32_bf16 v[84:87], v[92:95], v[16:19], v[84:87]
	s_waitcnt lgkmcnt(0)
	v_mfma_f32_16x16x32_bf16 v[150:153], v[212:215], v[4:7], v[88:91]
	v_mfma_f32_16x16x32_bf16 v[90:93], v[212:215], v[20:23], v[84:87]
	ds_read_b128 v[212:215], v83 offset:3456
	s_nop 3
	s_waitcnt lgkmcnt(0)
	v_mfma_f32_16x16x32_bf16 v[94:97], v[216:219], v[8:11], 0
	v_mfma_f32_16x16x32_bf16 v[84:87], v[216:219], v[12:15], 0
	ds_read_b128 v[216:219], v83 offset:6656
	v_mfma_f32_16x16x32_bf16 v[94:97], v[98:101], v[0:3], v[94:97]
	v_mfma_f32_16x16x32_bf16 v[84:87], v[98:101], v[16:19], v[84:87]
	s_waitcnt lgkmcnt(0)
	v_mfma_f32_16x16x32_bf16 v[158:161], v[212:215], v[4:7], v[94:97]
	v_mfma_f32_16x16x32_bf16 v[94:97], v[212:215], v[20:23], v[84:87]
	ds_read_b128 v[212:215], v83 offset:6784
	s_nop 3
	s_waitcnt lgkmcnt(0)
	v_mfma_f32_16x16x32_bf16 v[98:101], v[216:219], v[8:11], 0
	v_mfma_f32_16x16x32_bf16 v[84:87], v[216:219], v[12:15], 0
	ds_read_b128 v[216:219], v83 offset:9984
	v_mfma_f32_16x16x32_bf16 v[98:101], v[102:105], v[0:3], v[98:101]
	v_mfma_f32_16x16x32_bf16 v[84:87], v[102:105], v[16:19], v[84:87]
	s_waitcnt lgkmcnt(0)
	v_mfma_f32_16x16x32_bf16 v[166:169], v[212:215], v[4:7], v[98:101]
	v_mfma_f32_16x16x32_bf16 v[98:101], v[212:215], v[20:23], v[84:87]
	s_nop 3
	s_waitcnt lgkmcnt(0)
	v_mfma_f32_16x16x32_bf16 v[102:105], v[216:219], v[8:11], 0
	v_mfma_f32_16x16x32_bf16 v[84:87], v[216:219], v[12:15], 0
	v_mfma_f32_16x16x32_bf16 v[102:105], v[144:147], v[0:3], v[102:105]
	v_mfma_f32_16x16x32_bf16 v[84:87], v[144:147], v[16:19], v[84:87]
	ds_read_b128 v[144:147], v83 offset:10112
	v_max_f32_e32 v83, v151, v151
	s_waitcnt lgkmcnt(0)
	v_mfma_f32_16x16x32_bf16 v[178:181], v[144:147], v[4:7], v[102:105]
	v_mfma_f32_16x16x32_bf16 v[102:105], v[144:147], v[20:23], v[84:87]
	v_max_f32_e32 v145, v91, v91
	s_nop 1
	v_max_f32_e32 v84, v150, v150
	v_max_f32_e32 v83, v84, v83
	v_max_f32_e32 v84, v153, v153
	v_max_f32_e32 v85, v152, v152
	v_max_f32_e32 v84, v85, v84
	v_max_f32_e32 v85, v161, v161
	v_max_f32_e32 v86, v160, v160
	v_max_f32_e32 v85, v86, v85
	v_max3_f32 v85, v158, v159, v85
	v_max3_f32 v83, v83, v84, v85
	v_max_f32_e32 v84, v169, v169
	v_max_f32_e32 v85, v168, v168
	v_max_f32_e32 v84, v85, v84
	v_max_f32_e32 v85, v181, v181
	v_max_f32_e32 v86, v180, v180
	v_max_f32_e32 v85, v86, v85
	v_max3_f32 v84, v166, v167, v84
	v_max3_f32 v85, v178, v179, v85
	v_max3_f32 v83, v83, v84, v85
	s_waitcnt lgkmcnt(0)
	v_max_f32_e32 v84, v84, v84
	v_mov_b32_e32 v84, v83
	s_nop 1
	v_permlane16_swap_b32_e32 v83, v84
	v_max_f32_e32 v83, v83, v84
	v_mov_b32_e32 v84, v83
	s_nop 1
	v_permlane32_swap_b32_e32 v83, v84
	v_max3_f32 v176, v82, v83, v84
	v_sub_f32_e32 v82, v82, v176
	v_exp_f32_e32 v146, v82
	v_sub_f32_e32 v82, v150, v176
	v_exp_f32_e32 v142, v82
	v_sub_f32_e32 v82, v151, v176
	v_exp_f32_e32 v144, v82
	v_sub_f32_e32 v82, v152, v176
	v_exp_f32_e32 v150, v82
	v_sub_f32_e32 v82, v153, v176
	v_exp_f32_e32 v152, v82
	v_sub_f32_e32 v82, v158, v176
	v_exp_f32_e32 v156, v82
	v_sub_f32_e32 v82, v159, v176
	v_exp_f32_e32 v158, v82
	v_sub_f32_e32 v82, v160, v176
	v_exp_f32_e32 v160, v82
	v_sub_f32_e32 v82, v161, v176
	v_exp_f32_e32 v162, v82
	v_sub_f32_e32 v82, v166, v176
	v_exp_f32_e32 v164, v82
	v_sub_f32_e32 v82, v167, v176
	v_exp_f32_e32 v166, v82
	v_sub_f32_e32 v82, v168, v176
	v_exp_f32_e32 v168, v82
	v_sub_f32_e32 v82, v169, v176
	v_exp_f32_e32 v170, v82
	v_sub_f32_e32 v82, v178, v176
	v_exp_f32_e32 v172, v82
	v_sub_f32_e32 v82, v179, v176
	v_exp_f32_e32 v174, v82
	v_sub_f32_e32 v82, v180, v176
	v_exp_f32_e32 v178, v82
	v_sub_f32_e32 v82, v181, v176
	v_exp_f32_e32 v180, v82
	v_pk_mul_f32 v[84:85], v[68:69], v[146:147] op_sel_hi:[1,0]
	v_pk_mul_f32 v[82:83], v[66:67], v[146:147] op_sel_hi:[1,0]
	v_pk_mul_f32 v[88:89], v[72:73], v[146:147] op_sel_hi:[1,0]
	v_pk_mul_f32 v[86:87], v[70:71], v[146:147] op_sel_hi:[1,0]
	v_pk_mul_f32 v[76:77], v[76:77], v[146:147] op_sel_hi:[1,0]
	v_pk_mul_f32 v[74:75], v[74:75], v[146:147] op_sel_hi:[1,0]
	v_pk_mul_f32 v[68:69], v[80:81], v[146:147] op_sel_hi:[1,0]
	v_pk_mul_f32 v[66:67], v[78:79], v[146:147] op_sel_hi:[1,0]
	v_max_f32_e32 v147, v90, v90
	v_max_f32_e32 v145, v147, v145
	v_max_f32_e32 v147, v93, v93
	v_max_f32_e32 v151, v92, v92
	v_max_f32_e32 v147, v151, v147
	v_max_f32_e32 v151, v97, v97
	v_max_f32_e32 v153, v96, v96
	v_max_f32_e32 v151, v153, v151
	v_max3_f32 v151, v94, v95, v151
	v_max3_f32 v145, v145, v147, v151
	v_max_f32_e32 v147, v101, v101
	v_max_f32_e32 v151, v100, v100
	v_max_f32_e32 v147, v151, v147
	v_max_f32_e32 v151, v105, v105
	v_max_f32_e32 v153, v104, v104
	v_max_f32_e32 v151, v153, v151
	v_max3_f32 v147, v98, v99, v147
	v_max3_f32 v151, v102, v103, v151
	v_max3_f32 v145, v145, v147, v151
	v_cvt_pk_bf16_f32 v70, v142, v144
	v_cvt_pk_bf16_f32 v71, v150, v152
	v_cvt_pk_bf16_f32 v72, v156, v158
	v_cvt_pk_bf16_f32 v73, v160, v162
	s_waitcnt lgkmcnt(0)
	v_max_f32_e32 v147, v147, v147
	v_mov_b32_e32 v147, v145
	s_nop 1
	v_permlane16_swap_b32_e32 v145, v147
	v_max_f32_e32 v145, v145, v147
	v_mov_b32_e32 v147, v145
	s_nop 1
	v_permlane32_swap_b32_e32 v145, v147
	v_max3_f32 v177, v143, v145, v147
	v_sub_f32_e32 v143, v143, v177
	v_sub_f32_e32 v90, v90, v177
	v_exp_f32_e32 v147, v143
	v_exp_f32_e32 v143, v90
	v_sub_f32_e32 v90, v91, v177
	v_exp_f32_e32 v145, v90
	v_sub_f32_e32 v90, v92, v177
	v_exp_f32_e32 v151, v90
	v_sub_f32_e32 v90, v93, v177
	v_exp_f32_e32 v153, v90
	v_sub_f32_e32 v90, v94, v177
	v_exp_f32_e32 v157, v90
	v_sub_f32_e32 v90, v95, v177
	v_exp_f32_e32 v159, v90
	v_pk_add_f32 v[90:91], v[142:143], 0 op_sel_hi:[1,0]
	v_sub_f32_e32 v92, v96, v177
	v_pk_add_f32 v[90:91], v[144:145], v[90:91]
	v_exp_f32_e32 v161, v92
	v_pk_add_f32 v[90:91], v[150:151], v[90:91]
	v_sub_f32_e32 v92, v97, v177
	v_pk_add_f32 v[90:91], v[152:153], v[90:91]
	v_exp_f32_e32 v163, v92
	v_sub_f32_e32 v92, v98, v177
	v_pk_add_f32 v[90:91], v[156:157], v[90:91]
	v_exp_f32_e32 v165, v92
	v_sub_f32_e32 v92, v99, v177
	v_pk_add_f32 v[90:91], v[158:159], v[90:91]
	v_exp_f32_e32 v167, v92
	v_sub_f32_e32 v92, v100, v177
	v_exp_f32_e32 v169, v92
	v_sub_f32_e32 v92, v101, v177
	v_pk_add_f32 v[90:91], v[160:161], v[90:91]
	v_exp_f32_e32 v171, v92
	v_sub_f32_e32 v92, v102, v177
	v_pk_add_f32 v[90:91], v[162:163], v[90:91]
	v_exp_f32_e32 v173, v92
	v_sub_f32_e32 v92, v103, v177
	v_pk_add_f32 v[90:91], v[164:165], v[90:91]
	v_exp_f32_e32 v175, v92
	v_sub_f32_e32 v92, v104, v177
	v_pk_add_f32 v[90:91], v[166:167], v[90:91]
	v_exp_f32_e32 v179, v92
	v_sub_f32_e32 v92, v105, v177
	v_pk_add_f32 v[90:91], v[168:169], v[90:91]
	v_exp_f32_e32 v181, v92
	v_pk_add_f32 v[90:91], v[170:171], v[90:91]
	v_mov_b32_e32 v98, v147
	v_pk_add_f32 v[90:91], v[172:173], v[90:91]
	v_add3_u32 v142, s18, v127, v189
	ds_read_b64_tr_b16 v[216:217], v142 offset:13384
	ds_read_b64_tr_b16 v[218:219], v142 offset:15944
	ds_read_b64_tr_b16 v[212:213], v142 offset:13376
	ds_read_b64_tr_b16 v[214:215], v142 offset:15936
	v_pk_add_f32 v[90:91], v[174:175], v[90:91]
	v_pk_mul_f32 v[92:93], v[52:53], v[98:99] op_sel_hi:[1,0]
	v_pk_add_f32 v[90:91], v[178:179], v[90:91]
	v_pk_mul_f32 v[96:97], v[56:57], v[98:99] op_sel_hi:[1,0]
	v_pk_add_f32 v[90:91], v[180:181], v[90:91]
	v_pk_mul_f32 v[94:95], v[54:55], v[98:99] op_sel_hi:[1,0]
	v_pk_fma_f32 v[140:141], v[140:141], v[146:147], v[90:91]
	v_pk_mul_f32 v[90:91], v[50:51], v[98:99] op_sel_hi:[1,0]
	v_pk_mul_f32 v[60:61], v[60:61], v[98:99] op_sel_hi:[1,0]
	v_pk_mul_f32 v[58:59], v[58:59], v[98:99] op_sel_hi:[1,0]
	v_pk_mul_f32 v[52:53], v[64:65], v[98:99] op_sel_hi:[1,0]
	v_pk_mul_f32 v[50:51], v[62:63], v[98:99] op_sel_hi:[1,0]
	ds_read_b64_tr_b16 v[100:101], v142 offset:15872
	ds_read_b64_tr_b16 v[98:99], v142 offset:13312
	ds_read_b64_tr_b16 v[102:103], v142 offset:13320
	v_cvt_pk_bf16_f32 v54, v143, v145
	v_cvt_pk_bf16_f32 v55, v151, v153
	v_cvt_pk_bf16_f32 v56, v157, v159
	v_cvt_pk_bf16_f32 v57, v161, v163
	s_waitcnt lgkmcnt(1)
	v_mfma_f32_16x16x32_bf16 v[82:85], v[98:101], v[70:73], v[82:85]
	ds_read_b64_tr_b16 v[104:105], v142 offset:15880
	v_cvt_pk_bf16_f32 v78, v164, v166
	v_cvt_pk_bf16_f32 v79, v168, v170
	v_mfma_f32_16x16x32_bf16 v[90:93], v[98:101], v[54:57], v[90:93]
	v_cvt_pk_bf16_f32 v80, v172, v174
	v_cvt_pk_bf16_f32 v81, v178, v180
	s_waitcnt lgkmcnt(0)
	v_mfma_f32_16x16x32_bf16 v[74:77], v[212:215], v[70:73], v[74:77]
	v_cvt_pk_bf16_f32 v62, v165, v167
	v_cvt_pk_bf16_f32 v63, v169, v171
	v_cvt_pk_bf16_f32 v64, v173, v175
	v_mfma_f32_16x16x32_bf16 v[58:61], v[212:215], v[54:57], v[58:61]
	ds_read_b64_tr_b16 v[212:213], v142 offset:18432
	ds_read_b64_tr_b16 v[214:215], v142 offset:20992
	v_cvt_pk_bf16_f32 v65, v179, v181
	v_mov_b32_e32 v143, v177
	v_mfma_f32_16x16x32_bf16 v[86:89], v[102:105], v[70:73], v[86:89]
	ds_read_b64_tr_b16 v[220:221], v142 offset:18496
	ds_read_b64_tr_b16 v[222:223], v142 offset:21056
	v_mfma_f32_16x16x32_bf16 v[94:97], v[102:105], v[54:57], v[94:97]
	s_waitcnt lgkmcnt(0)
	v_mfma_f32_16x16x32_bf16 v[102:105], v[216:219], v[70:73], v[66:69]
	v_mfma_f32_16x16x32_bf16 v[98:101], v[216:219], v[54:57], v[50:53]
	s_nop 2
	ds_read_b64_tr_b16 v[54:55], v142 offset:18440
	ds_read_b64_tr_b16 v[56:57], v142 offset:21000
	s_waitcnt lgkmcnt(2)
	v_mfma_f32_16x16x32_bf16 v[66:69], v[212:215], v[78:81], v[82:85]
	s_nop 2
	s_waitcnt lgkmcnt(0)
	v_mfma_f32_16x16x32_bf16 v[74:77], v[220:223], v[78:81], v[74:77]
	v_mfma_f32_16x16x32_bf16 v[58:61], v[220:223], v[62:65], v[58:61]
	ds_read_b64_tr_b16 v[82:83], v142 offset:18504
	ds_read_b64_tr_b16 v[84:85], v142 offset:21064
	v_mfma_f32_16x16x32_bf16 v[50:53], v[212:215], v[62:65], v[90:93]
	v_mfma_f32_16x16x32_bf16 v[70:73], v[54:57], v[78:81], v[86:89]
	v_mfma_f32_16x16x32_bf16 v[54:57], v[54:57], v[62:65], v[94:97]
	s_waitcnt lgkmcnt(0)
	v_mfma_f32_16x16x32_bf16 v[78:81], v[82:85], v[78:81], v[102:105]
	v_mfma_f32_16x16x32_bf16 v[62:65], v[82:85], v[62:65], v[98:101]
	v_mov_b32_e32 v82, v176
	s_add_i32 s6, s46, -2
	s_cmp_ge_i32 s6, s52
	s_cbranch_scc1 .LBB0_1064
.LBB0_1078:
	s_and_b32 s6, s6, 3
	s_mulk_i32 s6, 0x5c00
	s_add_i32 s18, s6, 0
	v_add3_u32 v83, s18, v186, v188
	ds_read_b128 v[212:215], v83 offset:128
	ds_read_b128 v[84:87], v83
	ds_read_b128 v[92:95], v83 offset:64
	v_add3_u32 v127, s18, v127, v189
	s_waitcnt lgkmcnt(1)
	v_mfma_f32_16x16x32_bf16 v[88:91], v[84:87], v[8:11], 0
	ds_read_b128 v[98:101], v83 offset:3392
	ds_read_b128 v[102:105], v83 offset:6720
	ds_read_b128 v[144:147], v83 offset:10048
	v_mfma_f32_16x16x32_bf16 v[84:87], v[84:87], v[12:15], 0
	ds_read_b128 v[216:219], v83 offset:3328
	s_waitcnt lgkmcnt(3)
	v_mfma_f32_16x16x32_bf16 v[88:91], v[92:95], v[0:3], v[88:91]
	v_mfma_f32_16x16x32_bf16 v[84:87], v[92:95], v[16:19], v[84:87]
	s_waitcnt lgkmcnt(0)
	v_mfma_f32_16x16x32_bf16 v[150:153], v[212:215], v[4:7], v[88:91]
	v_mfma_f32_16x16x32_bf16 v[90:93], v[212:215], v[20:23], v[84:87]
	ds_read_b128 v[212:215], v83 offset:3456
	s_nop 3
	s_waitcnt lgkmcnt(0)
	v_mfma_f32_16x16x32_bf16 v[94:97], v[216:219], v[8:11], 0
	v_mfma_f32_16x16x32_bf16 v[84:87], v[216:219], v[12:15], 0
	ds_read_b128 v[216:219], v83 offset:6656
	v_mfma_f32_16x16x32_bf16 v[94:97], v[98:101], v[0:3], v[94:97]
	v_mfma_f32_16x16x32_bf16 v[84:87], v[98:101], v[16:19], v[84:87]
	s_waitcnt lgkmcnt(0)
	v_mfma_f32_16x16x32_bf16 v[158:161], v[212:215], v[4:7], v[94:97]
	v_mfma_f32_16x16x32_bf16 v[94:97], v[212:215], v[20:23], v[84:87]
	ds_read_b128 v[212:215], v83 offset:6784
	s_nop 3
	s_waitcnt lgkmcnt(0)
	v_mfma_f32_16x16x32_bf16 v[98:101], v[216:219], v[8:11], 0
	v_mfma_f32_16x16x32_bf16 v[84:87], v[216:219], v[12:15], 0
	ds_read_b128 v[216:219], v83 offset:9984
	v_mfma_f32_16x16x32_bf16 v[98:101], v[102:105], v[0:3], v[98:101]
	v_mfma_f32_16x16x32_bf16 v[84:87], v[102:105], v[16:19], v[84:87]
	s_waitcnt lgkmcnt(0)
	v_mfma_f32_16x16x32_bf16 v[166:169], v[212:215], v[4:7], v[98:101]
	v_mfma_f32_16x16x32_bf16 v[98:101], v[212:215], v[20:23], v[84:87]
	s_nop 3
	s_waitcnt lgkmcnt(0)
	v_mfma_f32_16x16x32_bf16 v[102:105], v[216:219], v[8:11], 0
	v_mfma_f32_16x16x32_bf16 v[84:87], v[216:219], v[12:15], 0
	v_mfma_f32_16x16x32_bf16 v[102:105], v[144:147], v[0:3], v[102:105]
	v_mfma_f32_16x16x32_bf16 v[84:87], v[144:147], v[16:19], v[84:87]
	ds_read_b64_tr_b16 v[212:213], v127 offset:13376
	ds_read_b64_tr_b16 v[214:215], v127 offset:15936
	ds_read_b128 v[144:147], v83 offset:10112
	v_max_f32_e32 v83, v151, v151
	s_waitcnt lgkmcnt(0)
	v_mfma_f32_16x16x32_bf16 v[176:179], v[144:147], v[4:7], v[102:105]
	v_mfma_f32_16x16x32_bf16 v[102:105], v[144:147], v[20:23], v[84:87]
	ds_read_b64_tr_b16 v[216:217], v127 offset:13384
	ds_read_b64_tr_b16 v[218:219], v127 offset:15944
	v_max_f32_e32 v145, v91, v91
	s_nop 1
	v_max_f32_e32 v84, v150, v150
	v_max_f32_e32 v83, v84, v83
	v_max_f32_e32 v84, v153, v153
	v_max_f32_e32 v85, v152, v152
	v_max_f32_e32 v84, v85, v84
	v_max_f32_e32 v85, v161, v161
	v_max_f32_e32 v86, v160, v160
	v_max_f32_e32 v85, v86, v85
	v_max3_f32 v85, v158, v159, v85
	v_max3_f32 v83, v83, v84, v85
	v_max_f32_e32 v84, v169, v169
	v_max_f32_e32 v85, v168, v168
	v_max_f32_e32 v84, v85, v84
	v_max_f32_e32 v85, v179, v179
	v_max_f32_e32 v86, v178, v178
	v_max_f32_e32 v85, v86, v85
	v_max3_f32 v84, v166, v167, v84
	v_max3_f32 v85, v176, v177, v85
	v_max3_f32 v83, v83, v84, v85
	s_waitcnt lgkmcnt(0)
	v_max_f32_e32 v84, v84, v84
	v_mov_b32_e32 v84, v83
	s_nop 1
	v_permlane16_swap_b32_e32 v83, v84
	v_max_f32_e32 v83, v83, v84
	v_mov_b32_e32 v84, v83
	s_nop 1
	v_permlane32_swap_b32_e32 v83, v84
	v_max3_f32 v174, v82, v83, v84
	v_sub_f32_e32 v82, v82, v174
	v_exp_f32_e32 v146, v82
	v_sub_f32_e32 v82, v150, v174
	v_exp_f32_e32 v142, v82
	v_sub_f32_e32 v82, v151, v174
	v_exp_f32_e32 v144, v82
	v_sub_f32_e32 v82, v152, v174
	v_exp_f32_e32 v150, v82
	v_sub_f32_e32 v82, v153, v174
	v_exp_f32_e32 v152, v82
	v_sub_f32_e32 v82, v158, v174
	v_exp_f32_e32 v156, v82
	v_sub_f32_e32 v82, v159, v174
	v_exp_f32_e32 v158, v82
	v_sub_f32_e32 v82, v160, v174
	v_exp_f32_e32 v160, v82
	v_sub_f32_e32 v82, v161, v174
	v_exp_f32_e32 v162, v82
	v_sub_f32_e32 v82, v166, v174
	v_exp_f32_e32 v164, v82
	v_sub_f32_e32 v82, v167, v174
	v_exp_f32_e32 v166, v82
	v_sub_f32_e32 v82, v168, v174
	v_exp_f32_e32 v168, v82
	v_sub_f32_e32 v82, v169, v174
	v_exp_f32_e32 v170, v82
	v_sub_f32_e32 v82, v176, v174
	v_exp_f32_e32 v172, v82
	v_sub_f32_e32 v82, v177, v174
	v_exp_f32_e32 v176, v82
	v_sub_f32_e32 v82, v178, v174
	v_exp_f32_e32 v178, v82
	v_sub_f32_e32 v82, v179, v174
	v_exp_f32_e32 v180, v82
	v_pk_mul_f32 v[84:85], v[68:69], v[146:147] op_sel_hi:[1,0]
	v_pk_mul_f32 v[82:83], v[66:67], v[146:147] op_sel_hi:[1,0]
	v_pk_mul_f32 v[88:89], v[72:73], v[146:147] op_sel_hi:[1,0]
	v_pk_mul_f32 v[86:87], v[70:71], v[146:147] op_sel_hi:[1,0]
	v_pk_mul_f32 v[76:77], v[76:77], v[146:147] op_sel_hi:[1,0]
	v_pk_mul_f32 v[74:75], v[74:75], v[146:147] op_sel_hi:[1,0]
	v_pk_mul_f32 v[68:69], v[80:81], v[146:147] op_sel_hi:[1,0]
	v_pk_mul_f32 v[66:67], v[78:79], v[146:147] op_sel_hi:[1,0]
	v_max_f32_e32 v147, v90, v90
	v_max_f32_e32 v145, v147, v145
	v_max_f32_e32 v147, v93, v93
	v_max_f32_e32 v151, v92, v92
	v_max_f32_e32 v147, v151, v147
	v_max_f32_e32 v151, v97, v97
	v_max_f32_e32 v153, v96, v96
	v_max_f32_e32 v151, v153, v151
	v_max3_f32 v151, v94, v95, v151
	v_max3_f32 v145, v145, v147, v151
	v_max_f32_e32 v147, v101, v101
	v_max_f32_e32 v151, v100, v100
	v_max_f32_e32 v147, v151, v147
	v_max_f32_e32 v151, v105, v105
	v_max_f32_e32 v153, v104, v104
	v_max_f32_e32 v151, v153, v151
	v_max3_f32 v147, v98, v99, v147
	v_max3_f32 v151, v102, v103, v151
	v_max3_f32 v145, v145, v147, v151
	v_cvt_pk_bf16_f32 v70, v142, v144
	v_cvt_pk_bf16_f32 v71, v150, v152
	v_cvt_pk_bf16_f32 v72, v156, v158
	v_cvt_pk_bf16_f32 v73, v160, v162
	s_waitcnt lgkmcnt(0)
	v_max_f32_e32 v147, v147, v147
	v_mov_b32_e32 v147, v145
	s_nop 1
	v_permlane16_swap_b32_e32 v145, v147
	v_max_f32_e32 v145, v145, v147
	v_mov_b32_e32 v147, v145
	s_nop 1
	v_permlane32_swap_b32_e32 v145, v147
	v_max3_f32 v175, v143, v145, v147
	v_sub_f32_e32 v143, v143, v175
	v_sub_f32_e32 v90, v90, v175
	v_exp_f32_e32 v147, v143
	v_exp_f32_e32 v143, v90
	v_sub_f32_e32 v90, v91, v175
	v_exp_f32_e32 v145, v90
	v_sub_f32_e32 v90, v92, v175
	v_exp_f32_e32 v151, v90
	v_sub_f32_e32 v90, v93, v175
	v_exp_f32_e32 v153, v90
	v_sub_f32_e32 v90, v94, v175
	v_exp_f32_e32 v157, v90
	v_sub_f32_e32 v90, v95, v175
	v_exp_f32_e32 v159, v90
	v_pk_add_f32 v[90:91], v[142:143], 0 op_sel_hi:[1,0]
	v_sub_f32_e32 v92, v96, v175
	v_pk_add_f32 v[90:91], v[144:145], v[90:91]
	v_exp_f32_e32 v161, v92
	v_pk_add_f32 v[90:91], v[150:151], v[90:91]
	v_sub_f32_e32 v92, v97, v175
	v_pk_add_f32 v[90:91], v[152:153], v[90:91]
	v_exp_f32_e32 v163, v92
	v_sub_f32_e32 v92, v98, v175
	v_pk_add_f32 v[90:91], v[156:157], v[90:91]
	v_exp_f32_e32 v165, v92
	v_sub_f32_e32 v92, v99, v175
	v_pk_add_f32 v[90:91], v[158:159], v[90:91]
	v_exp_f32_e32 v167, v92
	v_sub_f32_e32 v92, v100, v175
	v_exp_f32_e32 v169, v92
	v_sub_f32_e32 v92, v101, v175
	v_pk_add_f32 v[90:91], v[160:161], v[90:91]
	v_exp_f32_e32 v171, v92
	v_sub_f32_e32 v92, v102, v175
	v_pk_add_f32 v[90:91], v[162:163], v[90:91]
	v_exp_f32_e32 v173, v92
	v_sub_f32_e32 v92, v103, v175
	v_pk_add_f32 v[90:91], v[164:165], v[90:91]
	v_exp_f32_e32 v177, v92
	v_sub_f32_e32 v92, v104, v175
	v_pk_add_f32 v[90:91], v[166:167], v[90:91]
	v_exp_f32_e32 v179, v92
	v_sub_f32_e32 v92, v105, v175
	v_pk_add_f32 v[90:91], v[168:169], v[90:91]
	v_exp_f32_e32 v181, v92
	v_pk_add_f32 v[90:91], v[170:171], v[90:91]
	v_mov_b32_e32 v98, v147
	v_pk_add_f32 v[90:91], v[172:173], v[90:91]
	v_pk_mul_f32 v[92:93], v[52:53], v[98:99] op_sel_hi:[1,0]
	v_pk_add_f32 v[90:91], v[176:177], v[90:91]
	v_pk_mul_f32 v[96:97], v[56:57], v[98:99] op_sel_hi:[1,0]
	v_pk_add_f32 v[90:91], v[178:179], v[90:91]
	v_pk_mul_f32 v[94:95], v[54:55], v[98:99] op_sel_hi:[1,0]
	v_pk_add_f32 v[90:91], v[180:181], v[90:91]
	v_pk_mul_f32 v[60:61], v[60:61], v[98:99] op_sel_hi:[1,0]
	v_pk_fma_f32 v[140:141], v[140:141], v[146:147], v[90:91]
	v_pk_mul_f32 v[90:91], v[50:51], v[98:99] op_sel_hi:[1,0]
	v_pk_mul_f32 v[58:59], v[58:59], v[98:99] op_sel_hi:[1,0]
	v_pk_mul_f32 v[52:53], v[64:65], v[98:99] op_sel_hi:[1,0]
	v_pk_mul_f32 v[50:51], v[62:63], v[98:99] op_sel_hi:[1,0]
	ds_read_b64_tr_b16 v[100:101], v127 offset:15872
	ds_read_b64_tr_b16 v[98:99], v127 offset:13312
	ds_read_b64_tr_b16 v[102:103], v127 offset:13320
	v_cvt_pk_bf16_f32 v54, v143, v145
	v_cvt_pk_bf16_f32 v55, v151, v153
	v_cvt_pk_bf16_f32 v56, v157, v159
	v_cvt_pk_bf16_f32 v57, v161, v163
	s_waitcnt lgkmcnt(1)
	v_mfma_f32_16x16x32_bf16 v[82:85], v[98:101], v[70:73], v[82:85]
	ds_read_b64_tr_b16 v[104:105], v127 offset:15880
	v_cvt_pk_bf16_f32 v78, v164, v166
	v_cvt_pk_bf16_f32 v79, v168, v170
	v_mfma_f32_16x16x32_bf16 v[90:93], v[98:101], v[54:57], v[90:93]
	v_cvt_pk_bf16_f32 v80, v172, v176
	v_cvt_pk_bf16_f32 v81, v178, v180
	s_waitcnt lgkmcnt(0)
	v_mfma_f32_16x16x32_bf16 v[74:77], v[212:215], v[70:73], v[74:77]
	v_cvt_pk_bf16_f32 v62, v165, v167
	v_cvt_pk_bf16_f32 v63, v169, v171
	v_cvt_pk_bf16_f32 v64, v173, v177
	v_mfma_f32_16x16x32_bf16 v[58:61], v[212:215], v[54:57], v[58:61]
	ds_read_b64_tr_b16 v[212:213], v127 offset:18432
	ds_read_b64_tr_b16 v[214:215], v127 offset:20992
	v_cvt_pk_bf16_f32 v65, v179, v181
	v_mov_b32_e32 v143, v175
	v_mfma_f32_16x16x32_bf16 v[86:89], v[102:105], v[70:73], v[86:89]
	ds_read_b64_tr_b16 v[220:221], v127 offset:18496
	ds_read_b64_tr_b16 v[222:223], v127 offset:21056
	v_mfma_f32_16x16x32_bf16 v[94:97], v[102:105], v[54:57], v[94:97]
	s_waitcnt lgkmcnt(0)
	v_mfma_f32_16x16x32_bf16 v[102:105], v[216:219], v[70:73], v[66:69]
	v_mfma_f32_16x16x32_bf16 v[98:101], v[216:219], v[54:57], v[50:53]
	s_nop 2
	ds_read_b64_tr_b16 v[54:55], v127 offset:18440
	ds_read_b64_tr_b16 v[56:57], v127 offset:21000
	s_waitcnt lgkmcnt(2)
	v_mfma_f32_16x16x32_bf16 v[66:69], v[212:215], v[78:81], v[82:85]
	s_nop 2
	s_waitcnt lgkmcnt(0)
	v_mfma_f32_16x16x32_bf16 v[74:77], v[220:223], v[78:81], v[74:77]
	v_mfma_f32_16x16x32_bf16 v[58:61], v[220:223], v[62:65], v[58:61]
	ds_read_b64_tr_b16 v[82:83], v127 offset:18504
	ds_read_b64_tr_b16 v[84:85], v127 offset:21064
	v_mfma_f32_16x16x32_bf16 v[50:53], v[212:215], v[62:65], v[90:93]
	v_mfma_f32_16x16x32_bf16 v[70:73], v[54:57], v[78:81], v[86:89]
	v_mfma_f32_16x16x32_bf16 v[54:57], v[54:57], v[62:65], v[94:97]
	s_waitcnt lgkmcnt(0)
	v_mfma_f32_16x16x32_bf16 v[78:81], v[82:85], v[78:81], v[102:105]
	v_mfma_f32_16x16x32_bf16 v[62:65], v[82:85], v[62:65], v[98:101]
	v_mov_b32_e32 v82, v174
	s_branch .LBB0_1064
